# P1: redundant vmcnt(0) drain before the tile loop removed (the other GEMM phases have none; the prologue's vmcnt(6)+barrier already guards the first K-step)
# baseline (speedup 1.0000x reference)
; #define PG8_STAGE(bufoff, gbase, voff) do { _Pragma("unroll") for (int _i = 0; _i < 2; ++_i) \
;         __builtin_amdgcn_global_load_lds((const unsigned*)((const char*)(gbase) + (voff)[_i]), (LAS unsigned*)(lds + (bufoff) + ldsw + _i * 8192), 16, 0, 0); } while (0)
; #define PG8_WAIT_V(n) asm volatile("s_waitcnt vmcnt(" #n ")" ::: "memory")
; #define PG8_BAR __builtin_amdgcn_s_barrier()
; template <class Epi, class Sched>
; __device__ __forceinline__ void gemm_phase(LAS unsigned char* lds, const Gemm g, const Sched& S, const Epi& E) {
;     const int tid = threadIdx.x, wid = __builtin_amdgcn_readfirstlane(tid >> 6), lane = tid & 63, wr = wid >> 2, wc = wid & 3, fr = lane & 15, fq = lane >> 4;
;     const int K = g.K, nt = K / BK;
;     unsigned voffA[2], voffB[2];
; #pragma unroll
;     for (int i = 0; i < 2; ++i) { int R, C; stage_rc(tid * 16 + i * 8192, R, C); const int Rb = Epi::PERM ? ((R & ~31) + perm32(R & 31)) : R;
;         voffA[i] = (unsigned)(R * g.lda + C) * 2u; voffB[i] = (unsigned)(Rb * g.ldb + C) * 2u; }
;     const size_t kstep = (size_t)(BK * 2);
;     const size_t hstepA = (size_t)HALF * g.lda * 2, hstepB = (size_t)HALF * g.ldb * 2;
;     const size_t tstepA = 2 * hstepA, tstepB = 2 * hstepB;
;     const unsigned ldsw = (unsigned)wid * 1024u;
;     const int aoff = lds_byte(wr * 64 + fr, fq * 8), boff = lds_byte(wc * 32 + fr, fq * 8);
;     ...
;     Unit cur, nxt; int ui = 0;
;     if (!S.next(0, cur)) return;
;     f32x4 acc[2][2][4][2];
; #pragma unroll
;     for (int a = 0; a < 2; ++a)
; #pragma unroll
;         for (int b = 0; b < 2; ++b)
; #pragma unroll
;             for (int m = 0; m < 4; ++m)
; #pragma unroll
;                 for (int n = 0; n < 2; ++n) acc[a][b][m][n] = (f32x4){0.f, 0.f, 0.f, 0.f};
;     bf16x8 At[4][2], B0[2][2], B1[2][2];
;     const char* cA = (const char*)g.A + (size_t)cur.pm * tstepA + (size_t)cur.koffA * 2; const char* cB = (const char*)g.Bt + (size_t)cur.pn * tstepB + (size_t)cur.koffB * 2;
;     PG8_STAGE(PG8_SB(0, 0), cB, voffB); PG8_STAGE(PG8_SA(0, 0), cA, voffA); PG8_STAGE(PG8_SB(0, 1), cB + hstepB, voffB); PG8_STAGE(PG8_SA(0, 1), cA + hstepA, voffA);
;     if (wr == 1) PG8_BAR;
;     PG8_WAIT_V(4); PG8_BAR;
;     PG8_STAGE(PG8_SB(1, 0), cB + kstep, voffB); PG8_STAGE(PG8_SA(1, 0), cA + kstep, voffA); PG8_STAGE(PG8_SB(1, 1), cB + hstepB + kstep, voffB);
;     PG8_WAIT_V(6); PG8_BAR;
.LBB0_113:
	s_lshl_b32 s6, s6, 5
	s_mov_b64 s[8:9], 0x80
	s_and_b32 s11, s6, 0x60
	s_add_i32 m0, s17, 0x18000
	v_lshl_add_u64 v[6:7], v[6:7], 0, s[8:9]
	s_lshl_b32 s10, s5, 13
	s_lshl_b32 s12, s11, 7
	s_waitcnt vmcnt(4)
	s_barrier
	global_load_lds_dwordx4 v[6:7], off
	v_lshl_add_u64 v[4:5], v[4:5], 0, s[8:9]
	s_add_i32 m0, s17, 0x1a000
	s_add_i32 s33, s17, 0x8000
	s_add_i32 s34, s17, 0xa000
	global_load_lds_dwordx4 v[4:5], off
	v_lshl_add_u64 v[2:3], v[2:3], 0, s[8:9]
	s_mov_b32 m0, s33
	s_add_u32 s6, s24, 0x80080
	global_load_lds_dwordx4 v[2:3], off
	v_lshl_add_u64 v[0:1], v[0:1], 0, s[8:9]
	s_mov_b32 m0, s34
	s_addc_u32 s7, s25, 0
	global_load_lds_dwordx4 v[0:1], off
	s_add_i32 m0, s17, 0x1c000
	v_lshl_add_u64 v[0:1], s[6:7], 0, v[130:131]
	global_load_lds_dwordx4 v[0:1], off
	v_lshl_add_u64 v[0:1], s[6:7], 0, v[134:135]
	s_add_i32 m0, s17, 0x1e000
	s_waitcnt lgkmcnt(0)
	s_sext_i32_i8 s59, s4
	global_load_lds_dwordx4 v[0:1], off
	v_and_b32_e32 v0, 15, v196
	v_lshlrev_b32_e32 v1, 1, v11
	v_lshlrev_b32_e32 v2, 2, v196
	v_lshlrev_b32_e32 v3, 6, v196
	s_movk_i32 s4, 0x3c0
	v_lshl_or_b32 v144, s5, 6, v0
	v_lshl_or_b32 v0, v0, 6, v1
	v_and_b32_e32 v2, 32, v2
	v_and_or_b32 v1, v3, s4, v1
	v_bitop3_b32 v145, s12, v1, v2 bitop3:0xf6
	v_lshlrev_b32_e32 v1, 9, v196
	v_bitop3_b32 v0, v0, s10, v2 bitop3:0xde
	v_and_b32_e32 v1, 0x70000, v1
	v_lshlrev_b32_e32 v2, 12, v10
	v_or3_b32 v1, v8, v1, v2
	v_add_u32_e32 v136, v1, v9
	v_lshlrev_b32_e32 v1, 5, v12
	s_waitcnt vmcnt(6)
	v_and_b32_e32 v1, 0xf0000, v1
	v_or3_b32 v1, v8, v1, v2
	s_add_i32 s50, 0, 0x10000
	s_add_i32 s51, 0, 0x14000
	s_ashr_i32 s35, s3, 31
	v_or_b32_e32 v146, s11, v11
	v_mov_b32_e32 v137, v131
	v_add_u32_e32 v138, v1, v9
	v_mov_b32_e32 v139, v131
	v_mov_b64_e32 v[140:141], 0x252
	v_mov_b64_e32 v[142:143], 0x251
	v_add_u32_e32 v147, s50, v145
	v_add_u32_e32 v148, 0, v0
	v_add_u32_e32 v149, s51, v145
	s_movk_i32 s58, 0x2400
	s_barrier
	s_nop 0
